# mixer A: dead per-wave K-tile address arithmetic removed from the early prefetch block (72 of 156 instructions per unit), now that K comes from LDS
# speedup vs baseline: 1.0042x; 1.0042x over previous
; #define LAS __attribute__((address_space(3)))
; __device__ __forceinline__ void a_prefetch(const bf16* P, int un, int tid, int wave, int fr, int fq, v4u (&vpre)[4], bf16x8& Q0, bf16x8& Q1, bf16x8 (&K)[9][2]) {
;     int s0, sh, r, n, u0, hd; a_decode(un, s0, sh, r, n, u0, hd);
; #pragma unroll
;     for (int i = 0; i < 4; ++i) { const int e = tid + i * NTHREADS, kl = e >> 3, chunk = e & 7; int up = u0 - 64 + kl; up = up < 0 ? 0 : up; up = up > n - 1 ? n - 1 : up;
;         vpre[i] = *(const v4u*)(P + (size_t)(s0 + (up << sh) + r) * DIN + C_VA + hd * 64 + chunk * 8); }
;     { const int u = u0 + 16 * wave + fr; const bf16* qp = P + (size_t)(s0 + (u << sh) + r) * DIN + C_QA + hd * 64 + fq * 8; Q0 = *(const bf16x8*)qp; Q1 = *(const bf16x8*)(qp + 32); }
;     const int ub = u0 + 16 * wave - 64;
; #pragma unroll
;     for (int kt = 0; kt < 9; ++kt) { int up = ub + 16 * kt + fr; up = up < 0 ? 0 : up; up = up > n - 1 ? n - 1 : up;
;         const bf16* kp = P + (size_t)(s0 + (up << sh) + r) * DIN + C_KA + hd * 64 + fq * 8; K[kt][0] = *(const bf16x8*)kp; K[kt][1] = *(const bf16x8*)(kp + 32); }
; __device__ __forceinline__ void mixA_mfma(const bf16* P, bf16* OG, float* LSE, LAS unsigned char* lds, int bid, int G, int tid) {
;     ...
;     for (int un = bid; un < NU; un += G) {
;         int s0, sh, r, n, u0, hd; a_decode(un, s0, sh, r, n, u0, hd);
;         const float slope = exp2f(-8.0f * (float)(hd + 1) / 12.0f) * (float)(1 << sh) * L2E;
;         __syncthreads();
; #pragma unroll
;         for (int i = 0; i < 4; ++i) { const int e = tid + i * NTHREADS; *(LAS v4u*)(Vs + (e >> 3) * VROW + (e & 7) * 16) = vpre[i]; }
;         __syncthreads();
.LBB0_333:
	s_mul_hi_i32 s14, s78, 0x2aaaaaab
	s_lshr_b32 s15, s14, 31
	s_ashr_i32 s14, s14, 1
	s_waitcnt vmcnt(5)
	s_barrier
	ds_write_b128 v176, v[2:5]
	ds_write_b128 v177, v[6:9]
	ds_write_b128 v176, v[10:13] offset:20480
	ds_write_b128 v178, v[14:17]
	ds_write_b128 v176, v[240:243] offset:40960
	ds_write_b128 v177, v[244:247] offset:40960
	ds_write_b128 v176, v[248:251] offset:61440
	ds_write_b128 v178, v[252:255] offset:40960
	s_waitcnt lgkmcnt(0)
	s_barrier
	s_add_i32 s35, s78, s68
	s_cmpk_gt_i32 s35, 0x8ff
	s_cbranch_scc1 .Lamv_skip_0
	s_mul_hi_i32 s18, s35, 0x2aaaaaab
	s_lshr_b32 s19, s18, 31
	s_ashr_i32 s18, s18, 1
	s_add_i32 s18, s18, s19
	s_mul_i32 s19, s18, -12
	s_add_i32 s19, s35, s19
	s_lshl_b32 s24, s18, 7
	s_cmpk_lt_i32 s35, 0x600
	s_cselect_b32 s25, s3, 0x7ffff000
	s_cselect_b32 s36, s12, 0x1000
	s_and_b32 s25, s25, s24
	s_ashr_i32 s19, s19, 1
	s_sub_i32 s24, s24, s25
	s_and_b32 s37, s19, -2
	s_ashr_i32 s24, s24, 7
	s_lshl_b32 s19, -1, s37
	s_andn2_b32 s19, s24, s19
	s_ashr_i32 s24, s24, s37
	s_lshl_b32 s38, s24, 7
	s_sub_i32 s39, s38, 64
	s_add_i32 s38, s38, s22
	s_lshr_b32 s36, s36, s37
	v_add_u32_e32 v2, s39, v1
	v_add_u32_e32 v4, s39, v164
	v_add_u32_e32 v10, s39, v165
	v_add_u32_e32 v12, s39, v166
	s_add_i32 s36, s36, -1
	v_max_i32_e32 v2, 0, v2
	v_max_i32_e32 v4, 0, v4
	v_max_i32_e32 v10, 0, v10
	v_max_i32_e32 v12, 0, v12
	s_add_i32 s40, s19, s25
	s_mulk_i32 s18, 0xfd00
	s_add_i32 s19, s27, s29
	v_min_i32_e32 v2, s36, v2
	v_min_i32_e32 v4, s36, v4
	v_min_i32_e32 v10, s36, v10
	v_min_i32_e32 v12, s36, v12
	v_or_b32_e32 v202, s38, v207
	s_add_i32 s18, s19, s18
	v_lshlrev_b32_e32 v2, s37, v2
	v_lshlrev_b32_e32 v4, s37, v4
	v_lshlrev_b32_e32 v10, s37, v10
	v_lshlrev_b32_e32 v12, s37, v12
	v_lshlrev_b32_e32 v202, s37, v202
	s_ashr_i32 s19, s18, 31
	v_add_u32_e32 v2, s40, v2
	v_mov_b64_e32 v[90:91], s[74:75]
	v_add_u32_e32 v4, s40, v4
	v_add_u32_e32 v10, s40, v10
	v_add_u32_e32 v12, s40, v12
	v_add_u32_e32 v202, s40, v202
	v_mad_i64_i32 v[2:3], s[24:25], v2, s13, v[90:91]
	s_lshl_b64 s[18:19], s[18:19], 1
	v_mad_i64_i32 v[4:5], s[24:25], v4, s13, v[90:91]
	v_mad_i64_i32 v[10:11], s[24:25], v10, s13, v[90:91]
	v_mad_i64_i32 v[12:13], s[24:25], v12, s13, v[90:91]
	v_mad_i64_i32 v[202:203], s[24:25], v202, s13, v[90:91]
	v_lshl_add_u64 v[2:3], v[2:3], 0, s[18:19]
	v_mov_b32_e32 v159, v135
	v_lshl_add_u64 v[4:5], v[4:5], 0, s[18:19]
	v_lshl_add_u64 v[10:11], v[10:11], 0, s[18:19]
	v_lshl_add_u64 v[12:13], v[12:13], 0, s[18:19]
	v_lshl_add_u64 v[202:203], v[202:203], 0, s[18:19]
	v_mov_b32_e32 v161, v135
	v_lshl_add_u64 v[2:3], v[2:3], 0, v[158:159]
	v_lshl_add_u64 v[6:7], v[4:5], 0, v[158:159]
	v_lshl_add_u64 v[10:11], v[10:11], 0, v[158:159]
	v_lshl_add_u64 v[14:15], v[12:13], 0, v[158:159]
	v_lshl_add_u64 v[204:205], v[202:203], 0, v[160:161]
	global_load_dwordx4 v[240:243], v[2:3], off offset:1536
	global_load_dwordx4 v[244:247], v[6:7], off offset:1536
	global_load_dwordx4 v[248:251], v[10:11], off offset:1536
	global_load_dwordx4 v[252:255], v[14:15], off offset:1536
	global_load_dwordx4 v[2:5], v[2:3], off offset:3072
	s_nop 0
	global_load_dwordx4 v[6:9], v[6:7], off offset:3072
	s_nop 0
	global_load_dwordx4 v[10:13], v[10:11], off offset:3072
	s_nop 0
	global_load_dwordx4 v[14:17], v[14:15], off offset:3072
	s_nop 0
	s_nop 0

; #define LAS __attribute__((address_space(3)))
; __device__ __forceinline__ void a_prefetch(const bf16* P, int un, int tid, int wave, int fr, int fq, v4u (&vpre)[4], bf16x8& Q0, bf16x8& Q1, bf16x8 (&K)[9][2]) {
;     int s0, sh, r, n, u0, hd; a_decode(un, s0, sh, r, n, u0, hd);
; #pragma unroll
;     for (int i = 0; i < 4; ++i) { const int e = tid + i * NTHREADS, kl = e >> 3, chunk = e & 7; int up = u0 - 64 + kl; up = up < 0 ? 0 : up; up = up > n - 1 ? n - 1 : up;
;         vpre[i] = *(const v4u*)(P + (size_t)(s0 + (up << sh) + r) * DIN + C_VA + hd * 64 + chunk * 8); }
;     { const int u = u0 + 16 * wave + fr; const bf16* qp = P + (size_t)(s0 + (u << sh) + r) * DIN + C_QA + hd * 64 + fq * 8; Q0 = *(const bf16x8*)qp; Q1 = *(const bf16x8*)(qp + 32); }
;     const int ub = u0 + 16 * wave - 64;
; #pragma unroll
;     for (int kt = 0; kt < 9; ++kt) { int up = ub + 16 * kt + fr; up = up < 0 ? 0 : up; up = up > n - 1 ? n - 1 : up;
;         const bf16* kp = P + (size_t)(s0 + (up << sh) + r) * DIN + C_KA + hd * 64 + fq * 8; K[kt][0] = *(const bf16x8*)kp; K[kt][1] = *(const bf16x8*)(kp + 32); }
; __device__ __forceinline__ void mixA_mfma(const bf16* P, bf16* OG, float* LSE, LAS unsigned char* lds, int bid, int G, int tid) {
;     ...
;     for (int un = bid; un < NU; un += G) {
;         int s0, sh, r, n, u0, hd; a_decode(un, s0, sh, r, n, u0, hd);
;         const float slope = exp2f(-8.0f * (float)(hd + 1) / 12.0f) * (float)(1 << sh) * L2E;
;         __syncthreads();
; #pragma unroll
;         for (int i = 0; i < 4; ++i) { const int e = tid + i * NTHREADS; *(LAS v4u*)(Vs + (e >> 3) * VROW + (e & 7) * 16) = vpre[i]; }
;         __syncthreads();
.LBB0_1358:
	s_mul_hi_i32 s14, s33, 0x2aaaaaab
	s_lshr_b32 s15, s14, 31
	s_ashr_i32 s14, s14, 1
	s_waitcnt vmcnt(5)
	s_barrier
	ds_write_b128 v176, v[2:5]
	ds_write_b128 v177, v[6:9]
	ds_write_b128 v176, v[10:13] offset:20480
	ds_write_b128 v178, v[14:17]
	ds_write_b128 v176, v[240:243] offset:40960
	ds_write_b128 v177, v[244:247] offset:40960
	ds_write_b128 v176, v[248:251] offset:61440
	ds_write_b128 v178, v[252:255] offset:40960
	s_waitcnt lgkmcnt(0)
	s_barrier
	s_add_i32 s31, s33, s68
	s_cmpk_gt_i32 s31, 0x8ff
	s_cbranch_scc1 .Lamv_skip_1
	s_mul_hi_i32 s18, s31, 0x2aaaaaab
	s_lshr_b32 s19, s18, 31
	s_ashr_i32 s18, s18, 1
	s_add_i32 s18, s18, s19
	s_mul_i32 s19, s18, -12
	s_add_i32 s19, s31, s19
	s_lshl_b32 s35, s18, 7
	s_cmpk_lt_i32 s31, 0x600
	s_cselect_b32 s40, s12, 0x7ffff000
	s_cselect_b32 s41, s13, 0x1000
	s_and_b32 s40, s40, s35
	s_ashr_i32 s19, s19, 1
	s_sub_i32 s35, s35, s40
	s_and_b32 s42, s19, -2
	s_ashr_i32 s35, s35, 7
	s_lshl_b32 s19, -1, s42
	s_andn2_b32 s19, s35, s19
	s_ashr_i32 s35, s35, s42
	s_lshl_b32 s35, s35, 7
	s_sub_i32 s43, s35, 64
	s_add_i32 s35, s35, s21
	s_lshr_b32 s41, s41, s42
	v_add_u32_e32 v2, s43, v1
	v_add_u32_e32 v4, s43, v164
	v_add_u32_e32 v10, s43, v165
	v_add_u32_e32 v12, s43, v166
	s_add_i32 s50, s41, -1
	v_max_i32_e32 v2, 0, v2
	v_max_i32_e32 v4, 0, v4
	v_max_i32_e32 v10, 0, v10
	v_max_i32_e32 v12, 0, v12
	s_add_i32 s51, s19, s40
	s_mulk_i32 s18, 0xfd00
	s_add_i32 s19, s24, s25
	v_min_i32_e32 v2, s50, v2
	v_min_i32_e32 v4, s50, v4
	v_min_i32_e32 v10, s50, v10
	v_min_i32_e32 v12, s50, v12
	v_or_b32_e32 v202, s35, v213
	s_add_i32 s18, s19, s18
	v_lshlrev_b32_e32 v2, s42, v2
	v_lshlrev_b32_e32 v4, s42, v4
	v_lshlrev_b32_e32 v10, s42, v10
	v_lshlrev_b32_e32 v12, s42, v12
	v_lshlrev_b32_e32 v202, s42, v202
	s_ashr_i32 s19, s18, 31
	v_add_u32_e32 v2, s51, v2
	v_mov_b64_e32 v[90:91], s[74:75]
	v_add_u32_e32 v4, s51, v4
	v_add_u32_e32 v10, s51, v10
	v_add_u32_e32 v12, s51, v12
	v_add_u32_e32 v202, s51, v202
	v_mad_i64_i32 v[2:3], s[40:41], v2, s20, v[90:91]
	s_lshl_b64 s[18:19], s[18:19], 1
	v_mad_i64_i32 v[4:5], s[40:41], v4, s20, v[90:91]
	v_mad_i64_i32 v[10:11], s[40:41], v10, s20, v[90:91]
	v_mad_i64_i32 v[12:13], s[40:41], v12, s20, v[90:91]
	v_mad_i64_i32 v[202:203], s[40:41], v202, s20, v[90:91]
	v_lshl_add_u64 v[2:3], v[2:3], 0, s[18:19]
	v_mov_b32_e32 v159, v135
	v_lshl_add_u64 v[4:5], v[4:5], 0, s[18:19]
	v_lshl_add_u64 v[10:11], v[10:11], 0, s[18:19]
	v_lshl_add_u64 v[12:13], v[12:13], 0, s[18:19]
	v_lshl_add_u64 v[202:203], v[202:203], 0, s[18:19]
	v_mov_b32_e32 v161, v135
	v_lshl_add_u64 v[2:3], v[2:3], 0, v[158:159]
	v_lshl_add_u64 v[6:7], v[4:5], 0, v[158:159]
	v_lshl_add_u64 v[10:11], v[10:11], 0, v[158:159]
	v_lshl_add_u64 v[14:15], v[12:13], 0, v[158:159]
	v_lshl_add_u64 v[204:205], v[202:203], 0, v[160:161]
	global_load_dwordx4 v[240:243], v[2:3], off offset:1536
	global_load_dwordx4 v[244:247], v[6:7], off offset:1536
	global_load_dwordx4 v[248:251], v[10:11], off offset:1536
	global_load_dwordx4 v[252:255], v[14:15], off offset:1536
	global_load_dwordx4 v[2:5], v[2:3], off offset:3072
	s_nop 0
	global_load_dwordx4 v[6:9], v[6:7], off offset:3072
	s_nop 0
	global_load_dwordx4 v[10:13], v[10:11], off offset:3072
	s_nop 0
	global_load_dwordx4 v[14:17], v[14:15], off offset:3072
	s_nop 0
	s_nop 0
